# retention outputs: 2-byte stores replaced by LDS-transposed 16-byte stores, plus compacted row-sum stores
# speedup vs baseline: 1.0161x; 1.0161x over previous
.LBB0_612:
	v_lshrrev_b32_e32 v155, 6, v0
	v_lshrrev_b32_e32 v156, 8, v0
	v_add_u32_e32 v155, v155, v156
	v_mov_b32_e32 v156, 0x1dc00
	v_lshl_add_u32 v155, v155, 11, v156
	v_and_b32_e32 v156, 31, v0
	v_lshl_add_u32 v154, v156, 1, v155
	v_and_b32_e32 v157, 32, v0
	v_lshl_add_u32 v154, v157, 3, v154
	v_and_b32_e32 v160, 63, v0
	v_lshl_add_u32 v155, v160, 4, v155
	v_lshrrev_b32_e32 v161, 2, v160
	v_lshlrev_b32_e32 v161, 12, v161
	v_and_b32_e32 v162, 3, v0
	v_lshl_add_u32 v161, v162, 4, v161
	v_lshlrev_b32_e32 v156, 1, v156
	v_lshl_add_u32 v156, v157, 9, v156
	v_sub_u32_e32 v156, v161, v156
	v_add_u32_e32 v156, 0xfa00000, v156
	v_mul_f32_e32 v4, v228, v3
	v_exp_f32_e32 v7, v4
	v_lshl_add_u64 v[4:5], s[82:83], 0, v[184:185]
	v_mul_f32_e32 v8, v176, v7
	v_mul_f32_e32 v8, v50, v8
	s_nop 1
	v_fmac_f32_e32 v8, v66, v7
	v_bfe_u32 v7, v8, 16, 1
	v_add3_u32 v9, v8, v7, s1
	v_mul_f32_e32 v7, v229, v3
	v_exp_f32_e32 v10, v7
	ds_write_b16_d16_hi v154, v9
	v_mul_f32_e32 v7, v230, v3
	v_exp_f32_e32 v12, v7
	v_mul_f32_e32 v6, v176, v10
	v_mul_f32_e32 v11, v51, v6
	v_mul_f32_e32 v14, v231, v3
	v_mul_f32_e32 v13, v176, v12
	v_fmac_f32_e32 v11, v67, v10
	v_mul_f32_e32 v13, v52, v13
	v_exp_f32_e32 v14, v14
	v_bfe_u32 v6, v11, 16, 1
	v_fmac_f32_e32 v13, v68, v12
	v_add3_u32 v10, v11, v6, s1
	v_bfe_u32 v12, v13, 16, 1
	s_nop 0
	v_add3_u32 v12, v13, v12, s1
	ds_write_b16_d16_hi v154, v10 offset:64
	ds_write_b16_d16_hi v154, v12 offset:128
	v_mul_f32_e32 v6, v176, v14
	v_mul_f32_e32 v15, v53, v6
	v_fmac_f32_e32 v15, v69, v14
	v_bfe_u32 v6, v15, 16, 1
	v_add3_u32 v14, v15, v6, s1
	v_mul_f32_e32 v6, v232, v3
	v_exp_f32_e32 v16, v6
	v_mul_f32_e32 v52, v234, v3
	s_nop 0
	ds_write_b16_d16_hi v154, v14 offset:192
	v_mul_f32_e32 v6, v176, v16
	v_mul_f32_e32 v17, v54, v6
	v_fmac_f32_e32 v17, v70, v16
	v_bfe_u32 v6, v17, 16, 1
	v_add3_u32 v16, v17, v6, s1
	v_mul_f32_e32 v6, v233, v3
	v_exp_f32_e32 v50, v6
	v_exp_f32_e32 v52, v52
	v_mul_f32_e32 v51, v176, v50
	v_mul_f32_e32 v51, v55, v51
	v_fmac_f32_e32 v51, v71, v50
	v_bfe_u32 v50, v51, 16, 1
	v_add3_u32 v50, v51, v50, s1
	ds_write_b16_d16_hi v154, v16 offset:512
	ds_write_b16_d16_hi v154, v50 offset:576
	v_mul_f32_e32 v6, v176, v52
	v_mul_f32_e32 v53, v56, v6
	v_fmac_f32_e32 v53, v72, v52
	v_bfe_u32 v6, v53, 16, 1
	v_add3_u32 v52, v53, v6, s1
	v_mul_f32_e32 v6, v235, v3
	v_exp_f32_e32 v54, v6
	v_mul_f32_e32 v56, v236, v3
	v_exp_f32_e32 v56, v56
	v_mul_f32_e32 v55, v176, v54
	v_mul_f32_e32 v55, v57, v55
	v_fmac_f32_e32 v55, v73, v54
	v_bfe_u32 v54, v55, 16, 1
	s_nop 0
	v_add3_u32 v54, v55, v54, s1
	ds_write_b16_d16_hi v154, v52 offset:640
	ds_write_b16_d16_hi v154, v54 offset:704
	v_mul_f32_e32 v6, v176, v56
	v_mul_f32_e32 v57, v58, v6
	v_fmac_f32_e32 v57, v74, v56
	v_bfe_u32 v6, v57, 16, 1
	v_add3_u32 v56, v57, v6, s1
	v_mul_f32_e32 v6, v237, v3
	v_exp_f32_e32 v58, v6
	s_nop 0
	v_mul_f32_e32 v66, v176, v58
	v_mul_f32_e32 v59, v59, v66
	v_mul_f32_e32 v66, v238, v3
	v_exp_f32_e32 v66, v66
	v_fmac_f32_e32 v59, v75, v58
	v_bfe_u32 v58, v59, 16, 1
	v_add3_u32 v58, v59, v58, s1
	ds_write_b16_d16_hi v154, v56 offset:1024
	ds_write_b16_d16_hi v154, v58 offset:1088
	v_mul_f32_e32 v6, v176, v66
	v_mul_f32_e32 v60, v60, v6
	v_fmac_f32_e32 v60, v76, v66
	v_bfe_u32 v6, v60, 16, 1
	v_add3_u32 v66, v60, v6, s1
	v_mul_f32_e32 v6, v239, v3
	v_exp_f32_e32 v67, v6
	s_nop 0
	v_mul_f32_e32 v68, v176, v67
	v_mul_f32_e32 v61, v61, v68
	v_mul_f32_e32 v68, v240, v3
	v_exp_f32_e32 v68, v68
	v_fmac_f32_e32 v61, v77, v67
	v_bfe_u32 v67, v61, 16, 1
	v_add3_u32 v67, v61, v67, s1
	ds_write_b16_d16_hi v154, v66 offset:1152
	ds_write_b16_d16_hi v154, v67 offset:1216
	v_mul_f32_e32 v6, v176, v68
	v_mul_f32_e32 v62, v62, v6
	v_fmac_f32_e32 v62, v78, v68
	v_bfe_u32 v6, v62, 16, 1
	v_add3_u32 v68, v62, v6, s1
	v_mul_f32_e32 v6, v241, v3
	v_exp_f32_e32 v69, v6
	s_nop 0
	v_mul_f32_e32 v70, v176, v69
	v_mul_f32_e32 v63, v63, v70
	v_mul_f32_e32 v70, v242, v3
	v_mul_f32_e32 v3, v243, v3
	v_exp_f32_e32 v70, v70
	v_exp_f32_e32 v3, v3
	v_fmac_f32_e32 v63, v79, v69
	v_bfe_u32 v69, v63, 16, 1
	v_add3_u32 v69, v63, v69, s1
	ds_write_b16_d16_hi v154, v68 offset:1536
	ds_write_b16_d16_hi v154, v69 offset:1600
	v_mul_f32_e32 v7, v176, v70
	v_mul_f32_e32 v69, v176, v3
	v_mul_f32_e32 v7, v64, v7
	v_mul_f32_e32 v65, v65, v69
	v_fmac_f32_e32 v7, v80, v70
	v_fmac_f32_e32 v65, v81, v3
	v_bfe_u32 v64, v7, 16, 1
	v_bfe_u32 v3, v65, 16, 1
	v_mul_f32_e32 v9, v8, v8
	v_mul_f32_e32 v10, v11, v11
	v_add3_u32 v64, v7, v64, s1
	v_add3_u32 v3, v65, v3, s1
	v_mul_f32_e32 v12, v13, v13
	v_mul_f32_e32 v14, v15, v15
	v_mul_f32_e32 v16, v17, v17
	v_mul_f32_e32 v50, v51, v51
	ds_write_b16_d16_hi v154, v64 offset:1664
	ds_write_b16_d16_hi v154, v3 offset:1728
	v_add_co_u32_e32 v194, vcc, v4, v156
	s_nop 1
	v_addc_co_u32_e32 v195, vcc, 0, v5, vcc
	v_add_co_u32_e32 v196, vcc, 0x10000, v194
	s_nop 1
	v_addc_co_u32_e32 v197, vcc, 0, v195, vcc
	v_mov_b32_dpp v4, v9 row_shr:1 row_mask:0xf bank_mask:0xf bound_ctrl:1
	v_mov_b32_dpp v5, v10 row_shr:1 row_mask:0xf bank_mask:0xf bound_ctrl:1
	v_mul_f32_e32 v52, v53, v53
	v_mul_f32_e32 v54, v55, v55
	v_mul_f32_e32 v56, v57, v57
	v_mul_f32_e32 v58, v59, v59
	v_mul_f32_e32 v66, v60, v60
	v_mul_f32_e32 v67, v61, v61
	v_mul_f32_e32 v68, v62, v62
	v_mul_f32_e32 v6, v63, v63
	v_mul_f32_e32 v64, v7, v7
	v_mul_f32_e32 v3, v65, v65
	v_fmac_f32_e32 v4, v8, v8
	v_fmac_f32_e32 v5, v11, v11
	v_mov_b32_dpp v8, v12 row_shr:1 row_mask:0xf bank_mask:0xf bound_ctrl:1
	v_mov_b32_dpp v9, v14 row_shr:1 row_mask:0xf bank_mask:0xf bound_ctrl:1
	v_mov_b32_dpp v10, v16 row_shr:1 row_mask:0xf bank_mask:0xf bound_ctrl:1
	v_mov_b32_dpp v11, v50 row_shr:1 row_mask:0xf bank_mask:0xf bound_ctrl:1
	v_fmac_f32_e32 v8, v13, v13
	v_fmac_f32_e32 v9, v15, v15
	v_fmac_f32_e32 v10, v17, v17
	v_fmac_f32_e32 v11, v51, v51
	v_mov_b32_dpp v12, v52 row_shr:1 row_mask:0xf bank_mask:0xf bound_ctrl:1
	v_mov_b32_dpp v13, v54 row_shr:1 row_mask:0xf bank_mask:0xf bound_ctrl:1
	v_mov_b32_dpp v14, v56 row_shr:1 row_mask:0xf bank_mask:0xf bound_ctrl:1
	v_mov_b32_dpp v15, v58 row_shr:1 row_mask:0xf bank_mask:0xf bound_ctrl:1
	v_mov_b32_dpp v16, v66 row_shr:1 row_mask:0xf bank_mask:0xf bound_ctrl:1
	v_mov_b32_dpp v17, v67 row_shr:1 row_mask:0xf bank_mask:0xf bound_ctrl:1
	v_mov_b32_dpp v50, v68 row_shr:1 row_mask:0xf bank_mask:0xf bound_ctrl:1
	v_mov_b32_dpp v6, v6 row_shr:1 row_mask:0xf bank_mask:0xf bound_ctrl:1
	v_mov_b32_dpp v51, v64 row_shr:1 row_mask:0xf bank_mask:0xf bound_ctrl:1
	v_mov_b32_dpp v3, v3 row_shr:1 row_mask:0xf bank_mask:0xf bound_ctrl:1
	v_fmac_f32_e32 v12, v53, v53
	v_fmac_f32_e32 v13, v55, v55
	v_fmac_f32_e32 v14, v57, v57
	v_fmac_f32_e32 v15, v59, v59
	v_fmac_f32_e32 v16, v60, v60
	v_fmac_f32_e32 v17, v61, v61
	v_fmac_f32_e32 v50, v62, v62
	v_fmac_f32_e32 v6, v63, v63
	v_fmac_f32_e32 v51, v7, v7
	v_fmac_f32_e32 v3, v65, v65
	s_waitcnt lgkmcnt(0)
	ds_read_b128 v[160:163], v155
	ds_read_b128 v[164:167], v155 offset:1024
	v_add_f32_dpp v4, v4, v4 row_shr:2 row_mask:0xf bank_mask:0xf bound_ctrl:1
	v_add_f32_dpp v5, v5, v5 row_shr:2 row_mask:0xf bank_mask:0xf bound_ctrl:1
	v_add_f32_dpp v7, v8, v8 row_shr:2 row_mask:0xf bank_mask:0xf bound_ctrl:1
	v_add_f32_dpp v8, v9, v9 row_shr:2 row_mask:0xf bank_mask:0xf bound_ctrl:1
	v_add_f32_dpp v9, v10, v10 row_shr:2 row_mask:0xf bank_mask:0xf bound_ctrl:1
	v_add_f32_dpp v10, v11, v11 row_shr:2 row_mask:0xf bank_mask:0xf bound_ctrl:1
	v_add_f32_dpp v11, v12, v12 row_shr:2 row_mask:0xf bank_mask:0xf bound_ctrl:1
	v_add_f32_dpp v12, v13, v13 row_shr:2 row_mask:0xf bank_mask:0xf bound_ctrl:1
	v_add_f32_dpp v13, v14, v14 row_shr:2 row_mask:0xf bank_mask:0xf bound_ctrl:1
	v_add_f32_dpp v14, v15, v15 row_shr:2 row_mask:0xf bank_mask:0xf bound_ctrl:1
	v_add_f32_dpp v15, v16, v16 row_shr:2 row_mask:0xf bank_mask:0xf bound_ctrl:1
	v_add_f32_dpp v16, v17, v17 row_shr:2 row_mask:0xf bank_mask:0xf bound_ctrl:1
	v_add_f32_dpp v17, v50, v50 row_shr:2 row_mask:0xf bank_mask:0xf bound_ctrl:1
	v_add_f32_dpp v6, v6, v6 row_shr:2 row_mask:0xf bank_mask:0xf bound_ctrl:1
	v_add_f32_dpp v50, v51, v51 row_shr:2 row_mask:0xf bank_mask:0xf bound_ctrl:1
	v_add_f32_dpp v3, v3, v3 row_shr:2 row_mask:0xf bank_mask:0xf bound_ctrl:1
	v_add_f32_dpp v4, v4, v4 row_shr:4 row_mask:0xf bank_mask:0xf bound_ctrl:1
	v_add_f32_dpp v5, v5, v5 row_shr:4 row_mask:0xf bank_mask:0xf bound_ctrl:1
	v_add_f32_dpp v7, v7, v7 row_shr:4 row_mask:0xf bank_mask:0xf bound_ctrl:1
	v_add_f32_dpp v8, v8, v8 row_shr:4 row_mask:0xf bank_mask:0xf bound_ctrl:1
	v_add_f32_dpp v9, v9, v9 row_shr:4 row_mask:0xf bank_mask:0xf bound_ctrl:1
	v_add_f32_dpp v10, v10, v10 row_shr:4 row_mask:0xf bank_mask:0xf bound_ctrl:1
	v_add_f32_dpp v11, v11, v11 row_shr:4 row_mask:0xf bank_mask:0xf bound_ctrl:1
	v_add_f32_dpp v12, v12, v12 row_shr:4 row_mask:0xf bank_mask:0xf bound_ctrl:1
	v_add_f32_dpp v13, v13, v13 row_shr:4 row_mask:0xf bank_mask:0xf bound_ctrl:1
	v_add_f32_dpp v14, v14, v14 row_shr:4 row_mask:0xf bank_mask:0xf bound_ctrl:1
	v_add_f32_dpp v15, v15, v15 row_shr:4 row_mask:0xf bank_mask:0xf bound_ctrl:1
	v_add_f32_dpp v16, v16, v16 row_shr:4 row_mask:0xf bank_mask:0xf bound_ctrl:1
	v_add_f32_dpp v17, v17, v17 row_shr:4 row_mask:0xf bank_mask:0xf bound_ctrl:1
	v_add_f32_dpp v51, v6, v6 row_shr:4 row_mask:0xf bank_mask:0xf bound_ctrl:1
	v_add_f32_dpp v53, v50, v50 row_shr:4 row_mask:0xf bank_mask:0xf bound_ctrl:1
	v_add_f32_dpp v54, v3, v3 row_shr:4 row_mask:0xf bank_mask:0xf bound_ctrl:1
	v_add_f32_dpp v3, v4, v4 row_shr:8 row_mask:0xf bank_mask:0xf bound_ctrl:1
	v_add_f32_dpp v4, v5, v5 row_shr:8 row_mask:0xf bank_mask:0xf bound_ctrl:1
	v_add_f32_dpp v5, v7, v7 row_shr:8 row_mask:0xf bank_mask:0xf bound_ctrl:1
	v_add_f32_dpp v6, v8, v8 row_shr:8 row_mask:0xf bank_mask:0xf bound_ctrl:1
	v_add_f32_dpp v7, v9, v9 row_shr:8 row_mask:0xf bank_mask:0xf bound_ctrl:1
	v_add_f32_dpp v8, v10, v10 row_shr:8 row_mask:0xf bank_mask:0xf bound_ctrl:1
	v_add_f32_dpp v9, v11, v11 row_shr:8 row_mask:0xf bank_mask:0xf bound_ctrl:1
	v_add_f32_dpp v10, v12, v12 row_shr:8 row_mask:0xf bank_mask:0xf bound_ctrl:1
	v_add_f32_dpp v11, v13, v13 row_shr:8 row_mask:0xf bank_mask:0xf bound_ctrl:1
	v_add_f32_dpp v13, v14, v14 row_shr:8 row_mask:0xf bank_mask:0xf bound_ctrl:1
	v_add_f32_dpp v15, v15, v15 row_shr:8 row_mask:0xf bank_mask:0xf bound_ctrl:1
	v_add_f32_dpp v16, v16, v16 row_shr:8 row_mask:0xf bank_mask:0xf bound_ctrl:1
	v_add_f32_dpp v50, v17, v17 row_shr:8 row_mask:0xf bank_mask:0xf bound_ctrl:1
	v_add_f32_dpp v52, v51, v51 row_shr:8 row_mask:0xf bank_mask:0xf bound_ctrl:1
	v_add_f32_dpp v53, v53, v53 row_shr:8 row_mask:0xf bank_mask:0xf bound_ctrl:1
	v_add_f32_dpp v55, v54, v54 row_shr:8 row_mask:0xf bank_mask:0xf bound_ctrl:1
	s_waitcnt lgkmcnt(0)
	global_store_dwordx4 v[194:195], v[160:163], off
	global_store_dwordx4 v[196:197], v[164:167], off
	v_mov_b32_dpp v12, v3 quad_perm:[0,1,2,3] row_mask:0xf bank_mask:0x8
	v_mov_b32_dpp v12, v4 row_shl:1 row_mask:0xf bank_mask:0x8
	v_mov_b32_dpp v12, v5 row_shl:2 row_mask:0xf bank_mask:0x8
	v_mov_b32_dpp v12, v6 row_shl:3 row_mask:0xf bank_mask:0x8
	v_mov_b32_dpp v12, v7 row_shl:4 row_mask:0xf bank_mask:0x4
	v_mov_b32_dpp v12, v8 row_shl:5 row_mask:0xf bank_mask:0x4
	v_mov_b32_dpp v12, v9 row_shl:6 row_mask:0xf bank_mask:0x4
	v_mov_b32_dpp v12, v10 row_shl:7 row_mask:0xf bank_mask:0x4
	v_mov_b32_dpp v12, v11 row_shl:8 row_mask:0xf bank_mask:0x2
	v_mov_b32_dpp v12, v13 row_shl:9 row_mask:0xf bank_mask:0x2
	v_mov_b32_dpp v12, v15 row_shl:10 row_mask:0xf bank_mask:0x2
	v_mov_b32_dpp v12, v16 row_shl:11 row_mask:0xf bank_mask:0x2
	v_mov_b32_dpp v12, v50 row_shl:12 row_mask:0xf bank_mask:0x1
	v_mov_b32_dpp v12, v52 row_shl:13 row_mask:0xf bank_mask:0x1
	v_mov_b32_dpp v12, v53 row_shl:14 row_mask:0xf bank_mask:0x1
	v_mov_b32_dpp v12, v55 row_shl:15 row_mask:0xf bank_mask:0x1
	v_mov_b32_e32 v14, v12
	v_and_b32_e32 v50, 15, v0
	v_xor_b32_e32 v50, 15, v50
	v_lshrrev_b32_e32 v51, 2, v50
	v_and_b32_e32 v50, 3, v50
	v_lshlrev_b32_e32 v51, 11, v51
	v_lshl_or_b32 v50, v50, 8, v51
	v_add_u32_e32 v50, 0x200000, v50
	v_lshl_add_u64 v[4:5], s[82:83], 0, v[182:183]
	v_permlane16_swap_b32_e32 v12, v14
	v_add_co_u32_e32 v4, vcc, v4, v50
	v_add_f32_e32 v12, v12, v14
	s_nop 0
	v_addc_co_u32_e32 v5, vcc, 0, v5, vcc
	s_mov_b64 s[70:71], exec
	s_mov_b32 exec_lo, 0xffff
	s_mov_b32 exec_hi, 0xffff
	global_store_dword v[4:5], v12, off
	s_branch .LBB0_592
